# row passes: LN gamma/beta loaded once before the row loop, modulation vector loads issued together instead of 4 serialized round trips
# speedup vs baseline: 1.0207x; 1.0207x over previous
.LBB0_134:
	s_or_b64 exec, exec, s[4:5]
	v_mul_i32_i24_e32 v17, 0x1800, v23
	v_cndmask_b32_e64 v28, v17, v31, s[2:3]
	v_ashrrev_i32_e32 v29, 31, v28
	v_lshl_add_u64 v[28:29], v[28:29], 2, s[8:9]
	v_lshl_add_u64 v[40:41], v[28:29], 0, s[18:19]
	v_lshl_add_u64 v[32:33], v[40:41], 0, v[18:19]
	global_load_dwordx4 v[32:35], v[32:33], off
	v_lshl_add_u64 v[28:29], v[28:29], 0, v[18:19]
	global_load_dwordx4 v[36:39], v[28:29], off
	v_mad_i64_i32 v[42:43], s[2:3], v16, s30, v[20:21]
	v_mov_b32_e32 v23, v19
	v_lshl_add_u64 v[44:45], v[40:41], 0, v[22:23]
	v_mov_b32_e32 v25, v19
	v_mov_b32_e32 v27, v19
	v_add_u32_e32 v16, s25, v16
	v_cmp_lt_i32_e64 s[2:3], s31, v16
	s_or_b64 s[16:17], s[2:3], s[16:17]
	v_lshl_add_u64 v[102:103], v[40:41], 0, v[24:25]
	global_load_dwordx4 v[106:109], v[44:45], off
	global_load_dwordx4 v[110:113], v[28:29], off offset:1024
	v_lshl_add_u64 v[104:105], v[40:41], 0, v[26:27]
	global_load_dwordx4 v[114:117], v[102:103], off
	global_load_dwordx4 v[118:121], v[28:29], off offset:2048
	global_load_dwordx4 v[122:125], v[104:105], off
	global_load_dwordx4 v[126:129], v[28:29], off offset:3072
	s_waitcnt vmcnt(0)
	v_pk_add_f32 v[34:35], v[34:35], 1.0 op_sel_hi:[1,0]
	v_pk_add_f32 v[32:33], v[32:33], 1.0 op_sel_hi:[1,0]
	v_pk_fma_f32 v[14:15], v[14:15], v[34:35], v[38:39]
	v_pk_fma_f32 v[12:13], v[12:13], v[32:33], v[36:37]
	v_cvt_pk_bf16_f32 v12, v12, v13
	v_cvt_pk_bf16_f32 v13, v14, v15
	global_store_dwordx2 v[42:43], v[12:13], off
	s_nop 0
	v_pk_add_f32 v[108:109], v[108:109], 1.0 op_sel_hi:[1,0]
	v_pk_add_f32 v[106:107], v[106:107], 1.0 op_sel_hi:[1,0]
	v_pk_fma_f32 v[10:11], v[10:11], v[108:109], v[112:113]
	v_pk_fma_f32 v[8:9], v[8:9], v[106:107], v[110:111]
	v_cvt_pk_bf16_f32 v8, v8, v9
	v_cvt_pk_bf16_f32 v9, v10, v11
	global_store_dwordx2 v[42:43], v[8:9], off offset:512
	s_nop 0
	v_pk_add_f32 v[116:117], v[116:117], 1.0 op_sel_hi:[1,0]
	v_pk_add_f32 v[114:115], v[114:115], 1.0 op_sel_hi:[1,0]
	v_pk_fma_f32 v[6:7], v[6:7], v[116:117], v[120:121]
	v_pk_fma_f32 v[4:5], v[4:5], v[114:115], v[118:119]
	s_nop 0
	v_cvt_pk_bf16_f32 v4, v4, v5
	v_cvt_pk_bf16_f32 v5, v6, v7
	global_store_dwordx2 v[42:43], v[4:5], off offset:1024
	s_nop 0
	v_pk_add_f32 v[124:125], v[124:125], 1.0 op_sel_hi:[1,0]
	v_pk_add_f32 v[122:123], v[122:123], 1.0 op_sel_hi:[1,0]
	v_pk_fma_f32 v[2:3], v[2:3], v[124:125], v[128:129]
	v_pk_fma_f32 v[0:1], v[0:1], v[122:123], v[126:127]
	s_nop 0
	v_cvt_pk_bf16_f32 v0, v0, v1
	v_cvt_pk_bf16_f32 v1, v2, v3
	global_store_dwordx2 v[42:43], v[0:1], off offset:1536
	s_andn2_b64 exec, exec, s[16:17]
	s_cbranch_execz .LBB0_145

.LBB0_997:
	s_or_b64 exec, exec, s[2:3]
	v_readlane_b32 s6, v255, 2
	v_readlane_b32 s7, v255, 3
	s_waitcnt lgkmcnt(0)
	v_mov_b32_e32 v0, v190
	v_mov_b32_e32 v1, v190
	s_barrier
	s_mov_b32 s0, s94
	v_ashrrev_i32_e32 v1, 6, v1
	s_lshl_b32 s64, s26, 10
	v_lshl_add_u32 v16, s0, 3, v1
	s_movk_i32 s0, 0x4200
	s_mov_b32 s65, s55
	v_cmp_gt_i32_e32 vcc, s0, v16
	s_and_saveexec_b64 s[8:9], vcc
	s_cbranch_execz .LBB0_1008
	s_load_dwordx2 s[4:5], s[6:7], 0xf0
	v_readlane_b32 s10, v255, 2
	v_readlane_b32 s11, v255, 3
	s_load_dwordx4 s[0:3], s[10:11], 0xa8
	v_and_b32_e32 v1, 63, v0
	s_waitcnt lgkmcnt(0)
	s_add_u32 s10, s4, s62
	s_addc_u32 s11, s5, s63
	s_add_u32 s10, s10, 0x3180000
	s_addc_u32 s11, s11, 0
	s_lshl_b64 s[12:13], s[64:65], 2
	s_add_u32 s2, s2, s12
	s_addc_u32 s3, s3, s13
	s_add_u32 s0, s0, s12
	s_addc_u32 s1, s1, s13
	s_add_u32 s12, s4, 0x31aa000
	v_lshlrev_b32_e32 v176, 4, v1
	v_lshlrev_b32_e32 v18, 2, v1
	s_addc_u32 s13, s5, 0
	v_lshl_add_u64 v[20:21], s[0:1], 0, v[176:177]
	v_lshl_add_u64 v[22:23], s[2:3], 0, v[176:177]
	global_load_dwordx4 v[140:143], v[20:21], off
	global_load_dwordx4 v[144:147], v[22:23], off
	global_load_dwordx4 v[148:151], v[20:21], off offset:1024
	global_load_dwordx4 v[152:155], v[22:23], off offset:1024
	global_load_dwordx4 v[156:159], v[20:21], off offset:2048
	global_load_dwordx4 v[160:163], v[22:23], off offset:2048
	global_load_dwordx4 v[164:167], v[20:21], off offset:3072
	global_load_dwordx4 v[168:171], v[22:23], off offset:3072
	v_lshlrev_b32_e32 v176, 3, v1
	s_add_u32 s14, s4, 0xf37e000
	v_or_b32_e32 v0, 0x100, v18
	v_or_b32_e32 v2, 0x200, v18
	v_or_b32_e32 v4, 0x300, v18
	v_lshl_add_u64 v[6:7], s[4:5], 0, v[176:177]
	s_mov_b64 s[0:1], 0x33aa000
	v_cmp_eq_u32_e32 vcc, 0, v1
	s_addc_u32 s15, s5, 0
	v_lshl_add_u64 v[24:25], v[6:7], 0, s[0:1]
	s_mov_b64 s[16:17], 0
	v_lshlrev_b32_e32 v26, 2, v0
	v_lshlrev_b32_e32 v28, 2, v2
	v_lshlrev_b32_e32 v30, 2, v4
	s_branch .LBB0_1001
.LBB0_999:
	s_or_b64 exec, exec, s[0:1]
	v_mul_i32_i24_e32 v17, 0x1800, v19
	v_cndmask_b32_e64 v32, v17, v202, s[2:3]
	v_ashrrev_i32_e32 v33, 31, v32
	v_lshl_add_u64 v[32:33], v[32:33], 2, s[10:11]
	s_mov_b64 s[0:1], 0x3000
	v_lshl_add_u64 v[34:35], v[32:33], 0, s[0:1]
	s_mov_b64 s[0:1], 0x4000
	v_lshl_add_u64 v[32:33], v[32:33], 0, s[0:1]
	v_lshl_add_u64 v[36:37], v[34:35], 0, v[176:177]
	v_lshl_add_u64 v[40:41], v[32:33], 0, v[176:177]
	global_load_dwordx4 v[36:39], v[36:37], off
	v_mov_b32_e32 v27, v177
	global_load_dwordx4 v[40:43], v[40:41], off
	v_mov_b32_e32 v29, v177
	v_mov_b32_e32 v31, v177
	v_lshl_add_u64 v[102:103], v[34:35], 0, v[26:27]
	global_load_dwordx4 v[114:117], v[102:103], off
	v_lshl_add_u64 v[104:105], v[32:33], 0, v[26:27]
	global_load_dwordx4 v[118:121], v[104:105], off
	v_lshl_add_u64 v[108:109], v[32:33], 0, v[28:29]
	v_lshl_add_u64 v[106:107], v[34:35], 0, v[28:29]
	global_load_dwordx4 v[122:125], v[106:107], off
	global_load_dwordx4 v[126:129], v[108:109], off
	v_lshl_add_u64 v[112:113], v[32:33], 0, v[30:31]
	v_lshl_add_u64 v[110:111], v[34:35], 0, v[30:31]
	global_load_dwordx4 v[130:133], v[110:111], off
	global_load_dwordx4 v[134:137], v[112:113], off
	s_waitcnt vmcnt(0)
	v_pk_add_f32 v[42:43], v[42:43], 1.0 op_sel_hi:[1,0]
	v_pk_add_f32 v[40:41], v[40:41], 1.0 op_sel_hi:[1,0]
	v_pk_fma_f32 v[12:13], v[12:13], v[42:43], v[38:39]
	v_pk_fma_f32 v[14:15], v[14:15], v[40:41], v[36:37]
	s_nop 0
	v_cvt_pk_bf16_f32 v14, v14, v15
	v_cvt_pk_bf16_f32 v15, v12, v13
	v_mad_i64_i32 v[12:13], s[0:1], v16, s78, v[24:25]
	global_store_dwordx2 v[12:13], v[14:15], off
	v_pk_add_f32 v[14:15], v[120:121], 1.0 op_sel_hi:[1,0]
	v_pk_add_f32 v[118:119], v[118:119], 1.0 op_sel_hi:[1,0]
	v_pk_fma_f32 v[8:9], v[8:9], v[14:15], v[116:117]
	v_pk_fma_f32 v[10:11], v[10:11], v[118:119], v[114:115]
	v_cvt_pk_bf16_f32 v10, v10, v11
	v_cvt_pk_bf16_f32 v11, v8, v9
	global_store_dwordx2 v[12:13], v[10:11], off offset:512
	s_nop 0
	v_pk_add_f32 v[14:15], v[128:129], 1.0 op_sel_hi:[1,0]
	v_pk_add_f32 v[126:127], v[126:127], 1.0 op_sel_hi:[1,0]
	v_pk_fma_f32 v[4:5], v[4:5], v[14:15], v[124:125]
	v_pk_fma_f32 v[6:7], v[6:7], v[126:127], v[122:123]
	v_cvt_pk_bf16_f32 v6, v6, v7
	v_cvt_pk_bf16_f32 v7, v4, v5
	global_store_dwordx2 v[12:13], v[6:7], off offset:1024
	s_nop 0
	v_pk_add_f32 v[136:137], v[136:137], 1.0 op_sel_hi:[1,0]
	v_pk_add_f32 v[134:135], v[134:135], 1.0 op_sel_hi:[1,0]
	v_pk_fma_f32 v[0:1], v[0:1], v[136:137], v[132:133]
	v_pk_fma_f32 v[2:3], v[2:3], v[134:135], v[130:131]
	s_nop 0
	v_cvt_pk_bf16_f32 v2, v2, v3
	v_cvt_pk_bf16_f32 v3, v0, v1
	global_store_dwordx2 v[12:13], v[2:3], off offset:1536

.LBB0_1001:
	v_mul_hi_i32 v0, v16, s35
	v_lshrrev_b32_e32 v1, 31, v0
	v_ashrrev_i32_e32 v0, 11, v0
	v_add_u32_e32 v19, v0, v1
	v_mad_i32_i24 v1, v19, s33, v16
	v_cmp_gt_i32_e64 s[2:3], s95, v1
	s_and_b64 s[0:1], s[56:57], s[2:3]
	v_cmp_lt_i32_e64 s[4:5], s82, v1
	s_xor_b64 s[0:1], s[0:1], -1
	s_and_saveexec_b64 s[18:19], s[0:1]
	s_cbranch_execz .LBB0_1000
	s_and_saveexec_b64 s[0:1], s[4:5]
	s_xor_b64 s[0:1], exec, s[0:1]
	s_load_dwordx2 s[20:21], s[6:7], 0xe8
	v_mul_i32_i24_e32 v0, 0xffffdf00, v19
	v_lshl_add_u32 v0, v19, 13, v0
	v_add3_u32 v0, v16, v0, s79
	s_or_saveexec_b64 s[0:1], s[0:1]
	s_waitcnt lgkmcnt(0)
	v_mov_b64_e32 v[2:3], s[20:21]
	s_xor_b64 exec, exec, s[0:1]
	v_lshl_add_u32 v0, v19, 8, v1
	v_mov_b64_e32 v[2:3], s[12:13]
	s_or_b64 exec, exec, s[0:1]
	v_ashrrev_i32_e32 v1, 31, v0
	v_lshlrev_b64 v[0:1], 12, v[0:1]
	v_lshl_add_u64 v[0:1], v[2:3], 0, v[0:1]
	v_lshlrev_b32_e32 v176, 2, v18
	v_lshl_add_u64 v[32:33], v[0:1], 0, v[176:177]
	global_load_dwordx4 v[12:15], v[32:33], off
	global_load_dwordx4 v[8:11], v[32:33], off offset:1024
	global_load_dwordx4 v[4:7], v[32:33], off offset:2048
	global_load_dwordx4 v[0:3], v[32:33], off offset:3072
	v_and_b32_e32 v27, 64, v196
	v_add_u32_e32 v27, 64, v27
	v_xor_b32_e32 v29, 32, v196
	v_cmp_lt_i32_e64 s[4:5], v29, v27
	s_mov_b32 s0, 0x800000
	s_waitcnt vmcnt(3)
	v_mov_b32_e32 v34, v13
	v_mov_b32_e32 v35, v14
	v_mov_b32_e32 v36, v12
	v_mov_b32_e32 v37, v15
	v_pk_add_f32 v[34:35], v[34:35], v[36:37]
	s_waitcnt vmcnt(2)
	v_mov_b32_e32 v36, v9
	v_mov_b32_e32 v37, v10
	v_mov_b32_e32 v38, v8
	v_mov_b32_e32 v39, v11
	v_pk_add_f32 v[36:37], v[36:37], v[38:39]
	v_add_f32_e32 v17, v34, v35
	v_pk_add_f32 v[36:37], v[36:37], v[36:37] op_sel:[0,1] op_sel_hi:[1,0]
	v_add_f32_e32 v34, 0, v17
	s_waitcnt vmcnt(1)
	v_add_f32_e32 v38, v4, v5
	v_add_f32_e32 v40, v6, v7
	s_waitcnt vmcnt(0)
	v_mov_b32_e32 v35, v0
	v_mov_b32_e32 v37, v1
	v_mov_b32_e32 v39, v2
	v_mov_b32_e32 v41, v3
	v_pk_add_f32 v[34:35], v[34:35], v[36:37]
	v_pk_add_f32 v[36:37], v[38:39], v[40:41]
	v_cndmask_b32_e64 v29, v196, v29, s[4:5]
	v_pk_add_f32 v[34:35], v[34:35], v[36:37]
	v_lshlrev_b32_e32 v29, 2, v29
	v_add_f32_e32 v17, v34, v35
	ds_bpermute_b32 v31, v29, v17
	s_waitcnt lgkmcnt(0)
	v_add_f32_e32 v17, v17, v31
	v_xor_b32_e32 v31, 16, v196
	v_cmp_lt_i32_e64 s[4:5], v31, v27
	s_nop 1
	v_cndmask_b32_e64 v31, v196, v31, s[4:5]
	v_lshlrev_b32_e32 v31, 2, v31
	ds_bpermute_b32 v34, v31, v17
	s_waitcnt lgkmcnt(0)
	v_add_f32_e32 v17, v17, v34
	v_xor_b32_e32 v34, 8, v196
	v_cmp_lt_i32_e64 s[4:5], v34, v27
	s_nop 1
	v_cndmask_b32_e64 v34, v196, v34, s[4:5]
	v_lshlrev_b32_e32 v42, 2, v34
	ds_bpermute_b32 v34, v42, v17
	s_waitcnt lgkmcnt(0)
	v_add_f32_e32 v17, v17, v34
	v_xor_b32_e32 v34, 4, v196
	v_cmp_lt_i32_e64 s[4:5], v34, v27
	s_nop 1
	v_cndmask_b32_e64 v34, v196, v34, s[4:5]
	v_lshlrev_b32_e32 v43, 2, v34
	ds_bpermute_b32 v34, v43, v17
	s_waitcnt lgkmcnt(0)
	v_add_f32_e32 v17, v17, v34
	v_xor_b32_e32 v34, 2, v196
	v_cmp_lt_i32_e64 s[4:5], v34, v27
	s_nop 1
	v_cndmask_b32_e64 v34, v196, v34, s[4:5]
	v_lshlrev_b32_e32 v44, 2, v34
	ds_bpermute_b32 v34, v44, v17
	s_waitcnt lgkmcnt(0)
	v_add_f32_e32 v17, v17, v34
	v_xor_b32_e32 v34, 1, v196
	v_cmp_lt_i32_e64 s[4:5], v34, v27
	s_nop 1
	v_cndmask_b32_e64 v27, v196, v34, s[4:5]
	v_lshlrev_b32_e32 v27, 2, v27
	ds_bpermute_b32 v34, v27, v17
	s_waitcnt lgkmcnt(0)
	v_add_f32_e32 v17, v17, v34
	v_fmamk_f32 v13, v17, 0xba800000, v13
	v_fmamk_f32 v12, v17, 0xba800000, v12
	v_fmamk_f32 v15, v17, 0xba800000, v15
	v_fmac_f32_e32 v14, 0xba800000, v17
	v_pk_mul_f32 v[34:35], v[14:15], v[14:15]
	v_pk_mul_f32 v[36:37], v[12:13], v[12:13]
	v_fmamk_f32 v9, v17, 0xba800000, v9
	v_pk_mov_b32 v[38:39], v[36:37], v[34:35] op_sel:[1,0]
	v_mov_b32_e32 v37, v35
	v_pk_add_f32 v[34:35], v[38:39], v[36:37]
	v_fmamk_f32 v8, v17, 0xba800000, v8
	v_fmamk_f32 v11, v17, 0xba800000, v11
	v_fmac_f32_e32 v10, 0xba800000, v17
	v_pk_add_f32 v[34:35], v[34:35], v[34:35] op_sel_hi:[0,1]
	v_pk_mul_f32 v[36:37], v[10:11], v[10:11]
	v_pk_mul_f32 v[38:39], v[8:9], v[8:9]
	v_fmamk_f32 v4, v17, 0xba800000, v4
	v_pk_mov_b32 v[40:41], v[38:39], v[36:37] op_sel:[1,0]
	v_mov_b32_e32 v39, v37
	v_fmamk_f32 v5, v17, 0xba800000, v5
	v_fmac_f32_e32 v6, 0xba800000, v17
	v_mul_f32_e32 v34, v4, v4
	v_pk_add_f32 v[36:37], v[40:41], v[38:39]
	v_fmamk_f32 v7, v17, 0xba800000, v7
	v_pk_fma_f32 v[38:39], v[4:5], v[4:5], v[34:35] op_sel_hi:[1,1,0]
	v_mul_f32_e32 v34, v6, v6
	v_pk_add_f32 v[36:37], v[36:37], v[36:37] op_sel_hi:[0,1]
	v_pk_fma_f32 v[40:41], v[6:7], v[6:7], v[34:35] op_sel_hi:[1,1,0]
	v_fmamk_f32 v3, v17, 0xba800000, v3
	v_fmamk_f32 v2, v17, 0xba800000, v2
	v_fmamk_f32 v1, v17, 0xba800000, v1
	v_fmac_f32_e32 v0, 0xba800000, v17
	v_mul_f32_e32 v38, v0, v0
	v_mul_f32_e32 v40, v1, v1
	v_mul_f32_e32 v34, v2, v2
	v_mul_f32_e32 v36, v3, v3
	v_pk_add_f32 v[38:39], v[38:39], v[40:41]
	v_pk_add_f32 v[34:35], v[34:35], v[36:37]
	s_nop 0
	v_pk_add_f32 v[34:35], v[38:39], v[34:35]
	s_nop 0
	v_add_f32_e32 v17, v34, v35
	ds_bpermute_b32 v29, v29, v17
	s_waitcnt lgkmcnt(0)
	v_add_f32_e32 v17, v17, v29
	ds_bpermute_b32 v29, v31, v17
	s_waitcnt lgkmcnt(0)
	v_add_f32_e32 v17, v17, v29
	ds_bpermute_b32 v29, v42, v17
	s_waitcnt lgkmcnt(0)
	v_add_f32_e32 v17, v17, v29
	ds_bpermute_b32 v29, v43, v17
	s_waitcnt lgkmcnt(0)
	v_add_f32_e32 v17, v17, v29
	ds_bpermute_b32 v29, v44, v17
	s_waitcnt lgkmcnt(0)
	v_add_f32_e32 v17, v17, v29
	ds_bpermute_b32 v27, v27, v17
	s_waitcnt lgkmcnt(0)
	v_add_f32_e32 v17, v17, v27
	v_fmamk_f32 v17, v17, 0x3a800000, v197
	v_cmp_gt_f32_e64 s[4:5], s0, v17
	v_mul_f32_e32 v27, 0x4b800000, v17
	s_nop 0
	v_cndmask_b32_e64 v17, v17, v27, s[4:5]
	v_rsq_f32_e32 v17, v17
	s_nop 0
	v_mul_f32_e32 v27, 0x45800000, v17
	v_cndmask_b32_e64 v34, v17, v27, s[4:5]
	v_pk_mul_f32 v[44:45], v[12:13], v[34:35] op_sel_hi:[1,0]
	v_pk_mul_f32 v[12:13], v[14:15], v[34:35] op_sel_hi:[1,0]
	s_and_b64 s[4:5], s[2:3], s[60:61]
	v_ashrrev_i32_e32 v17, 31, v16
	v_pk_fma_f32 v[12:13], v[142:143], v[12:13], v[146:147]
	v_pk_fma_f32 v[14:15], v[140:141], v[44:45], v[144:145]
	v_pk_mul_f32 v[44:45], v[8:9], v[34:35] op_sel_hi:[1,0]
	v_pk_mul_f32 v[8:9], v[10:11], v[34:35] op_sel_hi:[1,0]
	v_pk_fma_f32 v[10:11], v[148:149], v[44:45], v[152:153]
	v_pk_fma_f32 v[8:9], v[150:151], v[8:9], v[154:155]
	v_pk_mul_f32 v[44:45], v[4:5], v[34:35] op_sel_hi:[1,0]
	v_pk_mul_f32 v[4:5], v[6:7], v[34:35] op_sel_hi:[1,0]
	v_pk_fma_f32 v[6:7], v[156:157], v[44:45], v[160:161]
	v_pk_fma_f32 v[4:5], v[158:159], v[4:5], v[162:163]
	v_pk_mul_f32 v[44:45], v[0:1], v[34:35] op_sel_hi:[1,0]
	v_pk_mul_f32 v[0:1], v[2:3], v[34:35] op_sel_hi:[1,0]
	v_pk_fma_f32 v[2:3], v[164:165], v[44:45], v[168:169]
	v_pk_fma_f32 v[0:1], v[166:167], v[0:1], v[170:171]
	v_cndmask_b32_e64 v38, 1.0, v252, s[4:5]
	v_pk_mul_f32 v[36:37], v[38:39], v[12:13] op_sel_hi:[0,1]
	v_pk_mul_f32 v[34:35], v[38:39], v[14:15] op_sel_hi:[0,1]
	global_store_dwordx4 v[32:33], v[34:37], off
	s_nop 1
	v_pk_mul_f32 v[36:37], v[38:39], v[8:9] op_sel_hi:[0,1]
	v_pk_mul_f32 v[34:35], v[38:39], v[10:11] op_sel_hi:[0,1]
	global_store_dwordx4 v[32:33], v[34:37], off offset:1024
	s_nop 1
	v_pk_mul_f32 v[36:37], v[38:39], v[4:5] op_sel_hi:[0,1]
	v_pk_mul_f32 v[34:35], v[38:39], v[6:7] op_sel_hi:[0,1]
	global_store_dwordx4 v[32:33], v[34:37], off offset:2048
	s_nop 1
	v_pk_mul_f32 v[36:37], v[38:39], v[0:1] op_sel_hi:[0,1]
	v_pk_mul_f32 v[34:35], v[38:39], v[2:3] op_sel_hi:[0,1]
	global_store_dwordx4 v[32:33], v[34:37], off offset:3072
	s_and_saveexec_b64 s[0:1], vcc
	s_cbranch_execz .LBB0_999
	v_mov_b32_e32 v34, v177
	v_lshl_add_u64 v[32:33], v[16:17], 3, s[14:15]
	s_nop 0
	v_mov_b32_e32 v35, v34
	global_store_dwordx2 v[32:33], v[34:35], off
	s_branch .LBB0_999

.LBB0_1483:
	s_or_b64 exec, exec, s[0:1]
	v_readlane_b32 s0, v255, 2
	v_readlane_b32 s1, v255, 3
	s_waitcnt lgkmcnt(0)
	v_mov_b32_e32 v0, v190
	v_mov_b32_e32 v1, v190
	s_barrier
	s_mov_b32 s2, s94
	v_ashrrev_i32_e32 v1, 6, v1
	s_nop 0
	v_lshl_add_u32 v16, s2, 3, v1
	s_movk_i32 s2, 0x4200
	v_cmp_gt_i32_e32 vcc, s2, v16
	s_and_saveexec_b64 s[6:7], vcc
	s_cbranch_execz .LBB0_1495
	s_load_dwordx2 s[4:5], s[0:1], 0xf0
	v_readlane_b32 s2, v255, 2
	v_readlane_b32 s3, v255, 3
	s_load_dwordx4 s[12:15], s[2:3], 0xd8
	v_and_b32_e32 v1, 63, v0
	s_waitcnt lgkmcnt(0)
	s_add_u32 s2, s4, s62
	s_addc_u32 s3, s5, s63
	s_add_u32 s8, s2, 0x3192000
	s_addc_u32 s9, s3, 0
	s_lshl_b64 s[2:3], s[64:65], 2
	s_add_u32 s14, s14, s2
	s_addc_u32 s15, s15, s3
	s_add_u32 s16, s12, s2
	s_addc_u32 s17, s13, s3
	s_add_u32 s10, s4, 0x31aa000
	s_addc_u32 s11, s5, 0
	v_lshlrev_b32_e32 v176, 4, v1
	v_lshlrev_b32_e32 v18, 2, v1
	s_add_u32 s12, s4, 0xf37e000
	v_lshl_add_u64 v[20:21], s[16:17], 0, v[176:177]
	v_lshl_add_u64 v[22:23], s[14:15], 0, v[176:177]
	global_load_dwordx4 v[140:143], v[20:21], off
	global_load_dwordx4 v[144:147], v[22:23], off
	global_load_dwordx4 v[148:151], v[20:21], off offset:1024
	global_load_dwordx4 v[152:155], v[22:23], off offset:1024
	global_load_dwordx4 v[156:159], v[20:21], off offset:2048
	global_load_dwordx4 v[160:163], v[22:23], off offset:2048
	global_load_dwordx4 v[164:167], v[20:21], off offset:3072
	global_load_dwordx4 v[168:171], v[22:23], off offset:3072
	v_lshlrev_b32_e32 v176, 3, v1
	s_addc_u32 s13, s5, 0
	v_or_b32_e32 v0, 0x100, v18
	v_or_b32_e32 v2, 0x200, v18
	v_or_b32_e32 v4, 0x300, v18
	v_lshl_add_u64 v[6:7], s[4:5], 0, v[176:177]
	s_mov_b64 s[4:5], 0x33aa000
	v_cmp_eq_u32_e64 s[2:3], 0, v1
	v_lshl_add_u64 v[24:25], v[6:7], 0, s[4:5]
	s_mov_b64 s[14:15], 0
	v_lshlrev_b32_e32 v26, 2, v0
	v_lshlrev_b32_e32 v28, 2, v2
	v_lshlrev_b32_e32 v30, 2, v4
	s_branch .LBB0_1487
.LBB0_1485:
	s_or_b64 exec, exec, s[18:19]
	v_mul_i32_i24_e32 v17, 0x1800, v19
	v_cndmask_b32_e64 v32, v17, v202, s[4:5]
	v_ashrrev_i32_e32 v33, 31, v32
	v_lshl_add_u64 v[32:33], v[32:33], 2, s[8:9]
	s_mov_b64 s[4:5], 0x1000
	v_lshl_add_u64 v[40:41], v[32:33], 0, s[4:5]
	v_lshl_add_u64 v[42:43], v[32:33], 0, v[176:177]
	v_lshl_add_u64 v[36:37], v[40:41], 0, v[176:177]
	global_load_dwordx4 v[32:35], v[42:43], off
	v_mov_b32_e32 v27, v177
	global_load_dwordx4 v[36:39], v[36:37], off
	v_mov_b32_e32 v29, v177
	v_mov_b32_e32 v31, v177
	v_lshl_add_u64 v[102:103], v[40:41], 0, v[26:27]
	global_load_dwordx4 v[108:111], v[42:43], off offset:1024
	global_load_dwordx4 v[112:115], v[102:103], off
	v_lshl_add_u64 v[104:105], v[40:41], 0, v[28:29]
	global_load_dwordx4 v[116:119], v[42:43], off offset:2048
	global_load_dwordx4 v[120:123], v[104:105], off
	v_lshl_add_u64 v[106:107], v[40:41], 0, v[30:31]
	global_load_dwordx4 v[124:127], v[42:43], off offset:3072
	global_load_dwordx4 v[128:131], v[106:107], off
	s_waitcnt vmcnt(0)
	v_pk_add_f32 v[38:39], v[38:39], 1.0 op_sel_hi:[1,0]
	v_pk_add_f32 v[36:37], v[36:37], 1.0 op_sel_hi:[1,0]
	v_pk_fma_f32 v[14:15], v[14:15], v[38:39], v[34:35]
	v_pk_fma_f32 v[12:13], v[12:13], v[36:37], v[32:33]
	v_mad_i64_i32 v[36:37], s[4:5], v16, s78, v[24:25]
	v_cvt_pk_bf16_f32 v12, v12, v13
	v_cvt_pk_bf16_f32 v13, v14, v15
	global_store_dwordx2 v[36:37], v[12:13], off
	s_nop 0
	v_pk_add_f32 v[114:115], v[114:115], 1.0 op_sel_hi:[1,0]
	v_pk_add_f32 v[112:113], v[112:113], 1.0 op_sel_hi:[1,0]
	v_pk_fma_f32 v[10:11], v[10:11], v[114:115], v[110:111]
	v_pk_fma_f32 v[8:9], v[8:9], v[112:113], v[108:109]
	v_cvt_pk_bf16_f32 v8, v8, v9
	v_cvt_pk_bf16_f32 v9, v10, v11
	global_store_dwordx2 v[36:37], v[8:9], off offset:512
	s_nop 0
	v_pk_add_f32 v[122:123], v[122:123], 1.0 op_sel_hi:[1,0]
	v_pk_add_f32 v[120:121], v[120:121], 1.0 op_sel_hi:[1,0]
	v_pk_fma_f32 v[6:7], v[6:7], v[122:123], v[118:119]
	v_pk_fma_f32 v[4:5], v[4:5], v[120:121], v[116:117]
	v_cvt_pk_bf16_f32 v4, v4, v5
	v_cvt_pk_bf16_f32 v5, v6, v7
	global_store_dwordx2 v[36:37], v[4:5], off offset:1024
	s_nop 0
	v_pk_add_f32 v[130:131], v[130:131], 1.0 op_sel_hi:[1,0]
	v_pk_add_f32 v[128:129], v[128:129], 1.0 op_sel_hi:[1,0]
	v_pk_fma_f32 v[2:3], v[2:3], v[130:131], v[126:127]
	v_pk_fma_f32 v[0:1], v[0:1], v[128:129], v[124:125]
	s_nop 0
	v_cvt_pk_bf16_f32 v0, v0, v1
	v_cvt_pk_bf16_f32 v1, v2, v3
	global_store_dwordx2 v[36:37], v[0:1], off offset:1536

.LBB0_1487:
	v_mul_hi_i32 v0, v16, s35
	v_lshrrev_b32_e32 v1, 31, v0
	v_ashrrev_i32_e32 v0, 11, v0
	v_add_u32_e32 v19, v0, v1
	v_mad_i32_i24 v1, v19, s33, v16
	v_cmp_gt_i32_e64 s[4:5], s95, v1
	s_and_b64 s[16:17], s[56:57], s[4:5]
	v_cmp_lt_i32_e32 vcc, s82, v1
	s_xor_b64 s[18:19], s[16:17], -1
	s_and_saveexec_b64 s[16:17], s[18:19]
	s_cbranch_execz .LBB0_1486
	s_and_saveexec_b64 s[18:19], vcc
	s_xor_b64 s[18:19], exec, s[18:19]
	s_load_dwordx2 s[20:21], s[0:1], 0xe8
	v_mul_i32_i24_e32 v0, 0xffffdf00, v19
	v_lshl_add_u32 v0, v19, 13, v0
	v_add3_u32 v0, v16, v0, s79
	s_or_saveexec_b64 s[18:19], s[18:19]
	s_waitcnt lgkmcnt(0)
	v_mov_b64_e32 v[2:3], s[20:21]
	s_xor_b64 exec, exec, s[18:19]
	v_lshl_add_u32 v0, v19, 8, v1
	v_mov_b64_e32 v[2:3], s[10:11]
	s_or_b64 exec, exec, s[18:19]
	v_ashrrev_i32_e32 v1, 31, v0
	v_lshlrev_b64 v[0:1], 12, v[0:1]
	v_lshl_add_u64 v[0:1], v[2:3], 0, v[0:1]
	v_lshlrev_b32_e32 v176, 2, v18
	v_lshl_add_u64 v[32:33], v[0:1], 0, v[176:177]
	global_load_dwordx4 v[12:15], v[32:33], off
	global_load_dwordx4 v[8:11], v[32:33], off offset:1024
	global_load_dwordx4 v[4:7], v[32:33], off offset:2048
	global_load_dwordx4 v[0:3], v[32:33], off offset:3072
	v_and_b32_e32 v27, 64, v196
	v_add_u32_e32 v27, 64, v27
	v_xor_b32_e32 v29, 32, v196
	v_cmp_lt_i32_e32 vcc, v29, v27
	s_mov_b32 s18, 0x800000
	s_waitcnt vmcnt(3)
	v_mov_b32_e32 v34, v13
	v_mov_b32_e32 v35, v14
	v_mov_b32_e32 v36, v12
	v_mov_b32_e32 v37, v15
	v_pk_add_f32 v[34:35], v[34:35], v[36:37]
	s_waitcnt vmcnt(2)
	v_mov_b32_e32 v36, v9
	v_mov_b32_e32 v37, v10
	v_mov_b32_e32 v38, v8
	v_mov_b32_e32 v39, v11
	v_pk_add_f32 v[36:37], v[36:37], v[38:39]
	v_add_f32_e32 v17, v34, v35
	v_pk_add_f32 v[36:37], v[36:37], v[36:37] op_sel:[0,1] op_sel_hi:[1,0]
	v_add_f32_e32 v34, 0, v17
	s_waitcnt vmcnt(1)
	v_add_f32_e32 v38, v4, v5
	v_add_f32_e32 v40, v6, v7
	s_waitcnt vmcnt(0)
	v_mov_b32_e32 v35, v0
	v_mov_b32_e32 v37, v1
	v_mov_b32_e32 v39, v2
	v_mov_b32_e32 v41, v3
	v_pk_add_f32 v[34:35], v[34:35], v[36:37]
	v_pk_add_f32 v[36:37], v[38:39], v[40:41]
	v_cndmask_b32_e32 v29, v196, v29, vcc
	v_pk_add_f32 v[34:35], v[34:35], v[36:37]
	v_lshlrev_b32_e32 v29, 2, v29
	v_add_f32_e32 v17, v34, v35
	ds_bpermute_b32 v31, v29, v17
	s_waitcnt lgkmcnt(0)
	v_add_f32_e32 v17, v17, v31
	v_xor_b32_e32 v31, 16, v196
	v_cmp_lt_i32_e32 vcc, v31, v27
	s_nop 1
	v_cndmask_b32_e32 v31, v196, v31, vcc
	v_lshlrev_b32_e32 v31, 2, v31
	ds_bpermute_b32 v34, v31, v17
	s_waitcnt lgkmcnt(0)
	v_add_f32_e32 v17, v17, v34
	v_xor_b32_e32 v34, 8, v196
	v_cmp_lt_i32_e32 vcc, v34, v27
	s_nop 1
	v_cndmask_b32_e32 v34, v196, v34, vcc
	v_lshlrev_b32_e32 v42, 2, v34
	ds_bpermute_b32 v34, v42, v17
	s_waitcnt lgkmcnt(0)
	v_add_f32_e32 v17, v17, v34
	v_xor_b32_e32 v34, 4, v196
	v_cmp_lt_i32_e32 vcc, v34, v27
	s_nop 1
	v_cndmask_b32_e32 v34, v196, v34, vcc
	v_lshlrev_b32_e32 v43, 2, v34
	ds_bpermute_b32 v34, v43, v17
	s_waitcnt lgkmcnt(0)
	v_add_f32_e32 v17, v17, v34
	v_xor_b32_e32 v34, 2, v196
	v_cmp_lt_i32_e32 vcc, v34, v27
	s_nop 1
	v_cndmask_b32_e32 v34, v196, v34, vcc
	v_lshlrev_b32_e32 v44, 2, v34
	ds_bpermute_b32 v34, v44, v17
	s_waitcnt lgkmcnt(0)
	v_add_f32_e32 v17, v17, v34
	v_xor_b32_e32 v34, 1, v196
	v_cmp_lt_i32_e32 vcc, v34, v27
	s_nop 1
	v_cndmask_b32_e32 v27, v196, v34, vcc
	v_lshlrev_b32_e32 v27, 2, v27
	ds_bpermute_b32 v34, v27, v17
	s_waitcnt lgkmcnt(0)
	v_add_f32_e32 v17, v17, v34
	v_fmamk_f32 v13, v17, 0xba800000, v13
	v_fmamk_f32 v12, v17, 0xba800000, v12
	v_fmamk_f32 v15, v17, 0xba800000, v15
	v_fmac_f32_e32 v14, 0xba800000, v17
	v_pk_mul_f32 v[34:35], v[14:15], v[14:15]
	v_pk_mul_f32 v[36:37], v[12:13], v[12:13]
	v_fmamk_f32 v9, v17, 0xba800000, v9
	v_pk_mov_b32 v[38:39], v[36:37], v[34:35] op_sel:[1,0]
	v_mov_b32_e32 v37, v35
	v_pk_add_f32 v[34:35], v[38:39], v[36:37]
	v_fmamk_f32 v8, v17, 0xba800000, v8
	v_fmamk_f32 v11, v17, 0xba800000, v11
	v_fmac_f32_e32 v10, 0xba800000, v17
	v_pk_add_f32 v[34:35], v[34:35], v[34:35] op_sel_hi:[0,1]
	v_pk_mul_f32 v[36:37], v[10:11], v[10:11]
	v_pk_mul_f32 v[38:39], v[8:9], v[8:9]
	v_fmamk_f32 v4, v17, 0xba800000, v4
	v_pk_mov_b32 v[40:41], v[38:39], v[36:37] op_sel:[1,0]
	v_mov_b32_e32 v39, v37
	v_fmamk_f32 v5, v17, 0xba800000, v5
	v_fmac_f32_e32 v6, 0xba800000, v17
	v_mul_f32_e32 v34, v4, v4
	v_pk_add_f32 v[36:37], v[40:41], v[38:39]
	v_fmamk_f32 v7, v17, 0xba800000, v7
	v_pk_fma_f32 v[38:39], v[4:5], v[4:5], v[34:35] op_sel_hi:[1,1,0]
	v_mul_f32_e32 v34, v6, v6
	v_pk_add_f32 v[36:37], v[36:37], v[36:37] op_sel_hi:[0,1]
	v_pk_fma_f32 v[40:41], v[6:7], v[6:7], v[34:35] op_sel_hi:[1,1,0]
	v_fmamk_f32 v3, v17, 0xba800000, v3
	v_fmamk_f32 v2, v17, 0xba800000, v2
	v_fmamk_f32 v1, v17, 0xba800000, v1
	v_fmac_f32_e32 v0, 0xba800000, v17
	v_mul_f32_e32 v38, v0, v0
	v_mul_f32_e32 v40, v1, v1
	v_mul_f32_e32 v34, v2, v2
	v_mul_f32_e32 v36, v3, v3
	v_pk_add_f32 v[38:39], v[38:39], v[40:41]
	v_pk_add_f32 v[34:35], v[34:35], v[36:37]
	s_nop 0
	v_pk_add_f32 v[34:35], v[38:39], v[34:35]
	s_nop 0
	v_add_f32_e32 v17, v34, v35
	ds_bpermute_b32 v29, v29, v17
	s_waitcnt lgkmcnt(0)
	v_add_f32_e32 v17, v17, v29
	ds_bpermute_b32 v29, v31, v17
	s_waitcnt lgkmcnt(0)
	v_add_f32_e32 v17, v17, v29
	ds_bpermute_b32 v29, v42, v17
	s_waitcnt lgkmcnt(0)
	v_add_f32_e32 v17, v17, v29
	ds_bpermute_b32 v29, v43, v17
	s_waitcnt lgkmcnt(0)
	v_add_f32_e32 v17, v17, v29
	ds_bpermute_b32 v29, v44, v17
	s_waitcnt lgkmcnt(0)
	v_add_f32_e32 v17, v17, v29
	ds_bpermute_b32 v27, v27, v17
	s_waitcnt lgkmcnt(0)
	v_add_f32_e32 v17, v17, v27
	v_fmamk_f32 v17, v17, 0x3a800000, v197
	v_cmp_gt_f32_e32 vcc, s18, v17
	v_mul_f32_e32 v27, 0x4b800000, v17
	s_nop 0
	v_cndmask_b32_e32 v17, v17, v27, vcc
	v_rsq_f32_e32 v17, v17
	s_nop 0
	v_mul_f32_e32 v27, 0x45800000, v17
	v_cndmask_b32_e32 v34, v17, v27, vcc
	v_pk_mul_f32 v[12:13], v[12:13], v[34:35] op_sel_hi:[1,0]
	v_pk_mul_f32 v[14:15], v[14:15], v[34:35] op_sel_hi:[1,0]
	v_pk_mul_f32 v[8:9], v[8:9], v[34:35] op_sel_hi:[1,0]
	v_pk_mul_f32 v[10:11], v[10:11], v[34:35] op_sel_hi:[1,0]
	v_pk_mul_f32 v[4:5], v[4:5], v[34:35] op_sel_hi:[1,0]
	v_pk_mul_f32 v[6:7], v[6:7], v[34:35] op_sel_hi:[1,0]
	v_pk_mul_f32 v[0:1], v[0:1], v[34:35] op_sel_hi:[1,0]
	v_pk_mul_f32 v[2:3], v[2:3], v[34:35] op_sel_hi:[1,0]
	s_andn2_b64 vcc, exec, s[60:61]
	v_pk_fma_f32 v[14:15], v[142:143], v[14:15], v[146:147]
	v_pk_fma_f32 v[12:13], v[140:141], v[12:13], v[144:145]
	v_pk_fma_f32 v[10:11], v[150:151], v[10:11], v[154:155]
	v_pk_fma_f32 v[8:9], v[148:149], v[8:9], v[152:153]
	v_pk_fma_f32 v[6:7], v[158:159], v[6:7], v[162:163]
	v_pk_fma_f32 v[4:5], v[156:157], v[4:5], v[160:161]
	v_pk_fma_f32 v[2:3], v[166:167], v[2:3], v[170:171]
	v_pk_fma_f32 v[0:1], v[164:165], v[0:1], v[168:169]
	global_store_dwordx4 v[32:33], v[12:15], off
	global_store_dwordx4 v[32:33], v[8:11], off offset:1024
	global_store_dwordx4 v[32:33], v[4:7], off offset:2048
	global_store_dwordx4 v[32:33], v[0:3], off offset:3072
	s_cbranch_vccnz .LBB0_1486
	v_ashrrev_i32_e32 v17, 31, v16
	s_and_saveexec_b64 s[18:19], s[2:3]
	s_cbranch_execz .LBB0_1485
	v_mov_b32_e32 v34, v177
	v_lshl_add_u64 v[32:33], v[16:17], 3, s[12:13]
	s_nop 0
	v_mov_b32_e32 v35, v34
	global_store_dwordx2 v[32:33], v[34:35], off
	s_branch .LBB0_1485
